# layers 0/1 mixing: memory-attention items moved to the workgroups that only had a scan unit; memKV GEMM workgroups skip theirs
# speedup vs baseline: 1.0412x; 1.0032x over previous
.LBB0_508:
	s_cmpk_lg_u32 s86, 0x100
	s_cbranch_scc1 .Lcnt_done
	s_and_b64 s[0:1], s[24:25], exec
	s_cbranch_scc0 .Lcnt_done
	s_cmp_lt_u32 s2, 100
	s_cselect_b32 s83, 1, s83
	s_sub_i32 s0, s2, 0x80
	s_cmp_lt_u32 s0, 100
	s_cselect_b32 s83, 2, s83
	v_readlane_b32 s1, v246, 0
	s_nop 1
	s_cmp_lg_u32 s1, 0
	s_cbranch_scc1 .Lcnt_done
	s_sub_i32 s0, s2, 100
	s_cmp_lt_u32 s0, 12
	s_cselect_b32 s83, 0, s83
	s_cmpk_gt_u32 s2, 0xf3
	s_cselect_b32 s83, 2, s83

.LBB0_511:
	s_not_b32 s0, s95
	s_add_i32 s3, s83, s0
	s_and_b64 s[0:1], s[24:25], exec
	s_cselect_b32 s0, s3, s95
	s_mul_i32 s22, s0, s86
	s_add_i32 s22, s22, s2
	s_cmpk_lg_u32 s86, 0x100
	s_cbranch_scc1 .Lit_done
	s_and_b64 s[0:1], s[24:25], exec
	s_cbranch_scc0 .Lit_done
	s_add_i32 s0, s2, 0x100
	s_cmp_lt_u32 s2, 100
	s_cselect_b32 s22, s0, s22
	s_sub_i32 s0, s2, 0x80
	s_cmp_eq_u32 s95, 0
	s_cselect_b32 s1, s2, s0
	s_cmp_lt_u32 s0, 100
	s_cselect_b32 s22, s1, s22
	v_readlane_b32 s0, v246, 0
	s_nop 1
	s_cmp_lg_u32 s0, 0
	s_cbranch_scc1 .Lit_done
	s_cmpk_lt_u32 s2, 0xf4
	s_cbranch_scc1 .Lit_done
	s_sub_i32 s0, s2, 0x90
	s_cmp_eq_u32 s95, 0
	s_cselect_b32 s22, s2, s0
.Lit_done:
	s_cmpk_gt_i32 s22, 0x7f
	s_cbranch_scc0 .LBB0_522
	v_readlane_b32 s0, v246, 18
	s_add_i32 s23, s22, 0xffffff80
	v_readlane_b32 s1, v246, 19
	s_and_b64 vcc, exec, s[0:1]
	s_mul_hi_u32 s8, s23, 0xaaaaaaab
	s_cbranch_vccz .LBB0_523
	s_lshr_b32 s33, s8, 3
	s_sub_i32 s6, 31, s33
	s_mul_i32 s0, s33, 12
	s_ashr_i32 s7, s6, 31
	s_sub_i32 s3, s23, s0
	s_lshl_b64 s[0:1], s[6:7], 21
	s_add_u32 s0, s16, s0
	s_addc_u32 s5, s17, s1
	s_lshl_b32 s1, s3, 7
	s_lshl_b32 s3, s3, 8
	s_waitcnt vmcnt(0)
	v_mov_b32_e32 v147, v181
	s_add_u32 s4, s0, s3
	s_addc_u32 s5, s5, 0
	v_and_b32_e32 v1, 15, v147
	s_waitcnt vmcnt(0)
	v_lshlrev_b32_e32 v150, 4, v1
	v_mov_b32_e32 v151, v0
	v_readfirstlane_b32 s0, v147
	v_lshlrev_b32_e32 v148, 3, v1
	v_lshl_add_u64 v[144:145], s[4:5], 0, v[150:151]
	v_add_u32_e32 v146, 0, v150
	s_mov_b32 s3, 0
